# v45 + dead lane-address math removed in step 5 + dt wait no longer drains previous chunk's stores
# speedup vs baseline: 1.0013x; 1.0013x over previous
.LBB0_336:
	v_readlane_b32 s98, v254, 52
	v_readlane_b32 s99, v254, 53
	v_readfirstlane_b32 s100, v158
	s_nop 3
	v_subrev_u32_e32 v2, s98, v176
	s_add_i32 s100, s100, s13
	s_lshl_b32 s100, s100, 13
	s_add_u32 s98, s98, s100
	s_addc_u32 s99, s99, 0
	s_add_u32 s98, s98, 0x1c000
	s_addc_u32 s99, s99, 0
	global_load_dword v108, v2, s[98:99]
	s_add_u32 s98, s98, 0x2000
	s_addc_u32 s99, s99, 0
	global_load_dword v107, v2, s[98:99]
	s_add_u32 s98, s98, 0x2000
	s_addc_u32 s99, s99, 0
	global_load_dword v106, v2, s[98:99]
	s_add_u32 s98, s98, 0x2000
	s_addc_u32 s99, s99, 0
	global_load_dword v105, v2, s[98:99]
	s_add_u32 s98, s98, 0x2000
	s_addc_u32 s99, s99, 0
	global_load_dword v104, v2, s[98:99]
	s_add_u32 s98, s98, 0x2000
	s_addc_u32 s99, s99, 0
	global_load_dword v103, v2, s[98:99]
	s_add_u32 s98, s98, 0x2000
	s_addc_u32 s99, s99, 0
	global_load_dword v102, v2, s[98:99]
	s_add_u32 s98, s98, 0x2000
	s_addc_u32 s99, s99, 0
	global_load_dword v101, v2, s[98:99]
	s_add_u32 s98, s98, 0x2000
	s_addc_u32 s99, s99, 0
	global_load_dword v100, v2, s[98:99]
	s_add_u32 s98, s98, 0x2000
	s_addc_u32 s99, s99, 0
	global_load_dword v99, v2, s[98:99]
	s_add_u32 s98, s98, 0x2000
	s_addc_u32 s99, s99, 0
	global_load_dword v98, v2, s[98:99]
	s_add_u32 s98, s98, 0x2000
	s_addc_u32 s99, s99, 0
	global_load_dword v97, v2, s[98:99]
	s_add_u32 s98, s98, 0x2000
	s_addc_u32 s99, s99, 0
	global_load_dword v96, v2, s[98:99]
	s_add_u32 s98, s98, 0x2000
	s_addc_u32 s99, s99, 0
	global_load_dword v95, v2, s[98:99]
	s_add_u32 s98, s98, 0x2000
	s_addc_u32 s99, s99, 0
	global_load_dword v94, v2, s[98:99]
	s_add_u32 s98, s98, 0x2000
	s_addc_u32 s99, s99, 0
	global_load_dword v3, v2, s[98:99]
	s_add_u32 s98, s98, 0x2000
	s_addc_u32 s99, s99, 0
	global_load_dword v69, v2, s[98:99]
	s_add_u32 s98, s98, 0x2000
	s_addc_u32 s99, s99, 0
	global_load_dword v71, v2, s[98:99]
	s_andn2_b64 vcc, exec, s[92:93]
	s_cbranch_vccnz .LBB0_340
	s_cmp_eq_u32 s13, 0
	s_cbranch_scc1 .Ldtw_first
	s_waitcnt vmcnt(39)
	s_branch .Ldtw_join
.Ldtw_first:
	s_waitcnt vmcnt(18)
.Ldtw_join:
	v_add_f32_e32 v2, v203, v153
	s_mov_b32 s14, 0x41a00000
	v_cmp_nlt_f32_e32 vcc, s14, v2
	s_and_saveexec_b64 s[94:95], vcc
	s_cbranch_execz .LBB0_339
	v_mul_f32_e32 v2, 0x3fb8aa3b, v2
	v_exp_f32_e32 v2, v2
	s_mov_b32 s14, 0x3f2aaaab
	v_add_f32_e32 v68, 1.0, v2
	v_frexp_mant_f32_e32 v74, v68
	v_cvt_f64_f32_e32 v[72:73], v68
	v_add_f32_e32 v70, -1.0, v68
	v_frexp_exp_i32_f64_e32 v72, v[72:73]
	v_cmp_gt_f32_e32 vcc, s14, v74
	v_sub_f32_e32 v75, v70, v68
	v_sub_f32_e32 v70, v2, v70
	v_subbrev_co_u32_e32 v80, vcc, 0, v72, vcc
	v_add_f32_e32 v75, 1.0, v75
	v_sub_u32_e32 v72, 0, v80
	v_add_f32_e32 v70, v70, v75
	v_ldexp_f32 v68, v68, v72
	v_ldexp_f32 v70, v70, v72
	v_add_f32_e32 v72, -1.0, v68
	v_add_f32_e32 v73, 1.0, v72
	v_sub_f32_e32 v73, v68, v73
	v_add_f32_e32 v74, v70, v73
	v_add_f32_e32 v73, 1.0, v68
	v_add_f32_e32 v75, -1.0, v73
	v_sub_f32_e32 v68, v68, v75
	v_add_f32_e32 v68, v70, v68
	v_add_f32_e32 v70, v73, v68
	v_rcp_f32_e32 v81, v70
	v_sub_f32_e32 v73, v70, v73
	v_sub_f32_e32 v68, v68, v73
	v_add_f32_e32 v73, v72, v74
	v_sub_f32_e32 v72, v73, v72
	v_mul_f32_e32 v83, v73, v81
	v_sub_f32_e32 v82, v74, v72
	v_mul_f32_e32 v74, v70, v83
	v_fma_f32 v76, v83, v70, -v74
	v_fmac_f32_e32 v76, v83, v68
	v_add_f32_e32 v72, v74, v76
	v_sub_f32_e32 v75, v73, v72
	v_pk_add_f32 v[78:79], v[72:73], v[74:75] neg_lo:[0,1] neg_hi:[0,1]
	v_mov_b32_e32 v77, v72
	v_pk_add_f32 v[72:73], v[78:79], v[76:77] neg_lo:[0,1] neg_hi:[0,1]
	s_mov_b32 s14, 0x3f317218
	v_add_f32_e32 v73, v82, v73
	v_add_f32_e32 v72, v72, v73
	v_add_f32_e32 v73, v75, v72
	v_mul_f32_e32 v82, v81, v73
	v_mul_f32_e32 v74, v70, v82
	v_fma_f32 v76, v82, v70, -v74
	v_fmac_f32_e32 v76, v82, v68
	v_sub_f32_e32 v68, v75, v73
	v_add_f32_e32 v68, v72, v68
	v_add_f32_e32 v72, v74, v76
	v_sub_f32_e32 v75, v73, v72
	v_pk_add_f32 v[78:79], v[72:73], v[74:75] neg_lo:[0,1] neg_hi:[0,1]
	v_mov_b32_e32 v77, v72
	v_pk_add_f32 v[72:73], v[78:79], v[76:77] neg_lo:[0,1] neg_hi:[0,1]
	v_add_f32_e32 v70, v83, v82
	v_add_f32_e32 v68, v68, v73
	v_add_f32_e32 v68, v72, v68
	v_add_f32_e32 v68, v75, v68
	v_sub_f32_e32 v72, v70, v83
	v_mul_f32_e32 v68, v81, v68
	v_sub_f32_e32 v72, v82, v72
	v_add_f32_e32 v68, v72, v68
	v_add_f32_e32 v73, v70, v68
	v_mul_f32_e32 v74, v73, v73
	v_fmamk_f32 v72, v74, 0x3e9b6dac, v193
	v_fmaak_f32 v153, v74, v72, 0x3f2aaada
	v_cvt_f32_i32_e32 v72, v80
	v_sub_f32_e32 v70, v73, v70
	v_ldexp_f32 v75, v73, 1
	v_mul_f32_e32 v73, v73, v74
	v_pk_mul_f32 v[76:77], v[72:73], v[152:153]
	v_sub_f32_e32 v68, v68, v70
	v_fma_f32 v74, v72, s14, -v76
	v_fmac_f32_e32 v74, 0xb102e308, v72
	v_pk_add_f32 v[72:73], v[76:77], v[74:75]
	v_ldexp_f32 v68, v68, 1
	v_sub_f32_e32 v70, v73, v75
	v_sub_f32_e32 v70, v77, v70
	v_add_f32_e32 v79, v68, v70
	v_mov_b32_e32 v78, v76
	v_pk_add_f32 v[76:77], v[72:73], v[76:77] neg_lo:[0,1] neg_hi:[0,1]
	v_pk_add_f32 v[80:81], v[72:73], v[78:79]
	v_mov_b32_e32 v75, v72
	v_mov_b32_e32 v77, v81
	v_pk_add_f32 v[82:83], v[74:75], v[76:77] neg_lo:[0,1] neg_hi:[0,1]
	v_pk_add_f32 v[74:75], v[74:75], v[76:77]
	v_mov_b32_e32 v78, v79
	v_pk_add_f32 v[76:77], v[74:75], v[72:73] op_sel:[1,0] op_sel_hi:[0,1] neg_lo:[0,1] neg_hi:[0,1]
	v_pk_add_f32 v[84:85], v[80:81], v[76:77] op_sel_hi:[1,0] neg_lo:[0,1] neg_hi:[0,1]
	v_mov_b32_e32 v80, v81
	v_mov_b32_e32 v81, v75
	v_pk_mov_b32 v[76:77], v[72:73], v[76:77] op_sel:[1,0]
	v_mov_b32_e32 v79, v72
	v_pk_add_f32 v[76:77], v[80:81], v[76:77] neg_lo:[0,1] neg_hi:[0,1]
	v_mov_b32_e32 v84, v82
	v_pk_add_f32 v[72:73], v[78:79], v[76:77] neg_lo:[0,1] neg_hi:[0,1]
	v_mov_b32_e32 v83, v75
	v_pk_add_f32 v[76:77], v[84:85], v[72:73]
	s_mov_b32 s14, 0x7f800000
	v_pk_add_f32 v[78:79], v[76:77], v[76:77] op_sel:[0,1] op_sel_hi:[1,0]
	v_cmp_neq_f32_e32 vcc, s14, v2
	v_pk_add_f32 v[74:75], v[74:75], v[78:79] op_sel:[1,0] op_sel_hi:[0,1]
	v_mov_b32_e32 v77, v74
	v_pk_add_f32 v[80:81], v[76:77], v[82:83] neg_lo:[0,1] neg_hi:[0,1]
	v_mov_b32_e32 v73, v78
	v_sub_f32_e32 v68, v76, v80
	v_pk_add_f32 v[72:73], v[72:73], v[80:81] neg_lo:[0,1] neg_hi:[0,1]
	v_sub_f32_e32 v68, v82, v68
	v_add_f32_e32 v68, v72, v68
	v_add_f32_e32 v68, v68, v73
	v_add_f32_e32 v68, v74, v68
	v_cndmask_b32_e32 v68, v196, v68, vcc
	v_cmp_ngt_f32_e32 vcc, -1.0, v2
	s_mov_b32 s14, 0x33800000
	s_nop 0
	v_cndmask_b32_e32 v68, v197, v68, vcc
	v_cmp_neq_f32_e32 vcc, -1.0, v2
	s_nop 1
	v_cndmask_b32_e32 v68, v198, v68, vcc
	v_cmp_lt_f32_e64 vcc, |v2|, s14
	s_nop 1
	v_cndmask_b32_e32 v2, v68, v2, vcc

.LBB0_380:
	s_or_b64 exec, exec, s[94:95]
	s_add_i32 s14, s15, 1
	s_cmp_lt_u32 s14, s0
	s_cselect_b32 s15, s14, s15
	s_lshl_b32 s16, s15, 6
	v_add_u32_e32 v2, s13, v231
	s_add_i32 s16, s16, s97
	v_ashrrev_i32_e32 v3, 31, v2
	s_cmp_eq_u32 s15, 0
	v_lshlrev_b64 v[2:3], 12, v[2:3]
	s_cselect_b32 s15, 0, 0x1000
	v_lshl_add_u64 v[190:191], v[164:165], 0, v[2:3]
	global_load_dwordx4 v[76:79], v[190:191], off
	global_load_dwordx4 v[80:83], v[190:191], off offset:128
	global_load_dwordx4 v[72:75], v[190:191], off offset:256
	global_load_dwordx4 v[68:71], v[190:191], off offset:384
	s_waitcnt lgkmcnt(0)
	s_barrier
	v_readlane_b32 s98, v254, 52
	v_readlane_b32 s99, v254, 53
	v_readfirstlane_b32 s100, v1
	s_nop 3
	v_subrev_u32_e32 v151, s98, v176
	s_cmp_lg_u32 s100, 0
	s_cselect_b32 s101, 0x1000, s15
	s_add_i32 s100, s100, s16
	s_lshl_b32 s100, s100, 13
	s_add_u32 s98, s98, s100
	s_addc_u32 s99, s99, 0
	s_mul_i32 s100, s101, 6
	s_sub_u32 s98, s98, s100
	s_subb_u32 s99, s99, 0
	s_lshl_b32 s100, s101, 1
	v_add_u32_e32 v2, s16, v159
	v_ashrrev_i32_e32 v3, 31, v2
	v_lshlrev_b64 v[2:3], 7, v[2:3]
	v_lshl_add_u64 v[2:3], s[90:91], 0, v[2:3]
	global_load_dword v153, v[2:3], off
	ds_read_b128 v[84:87], v180
	ds_read_b128 v[88:91], v181 offset:17408
	ds_read_b128 v[92:95], v181 offset:21760
	global_load_dword v250, v151, s[98:99]
	ds_read_b128 v[104:107], v180 offset:64
	ds_read_b128 v[96:99], v181 offset:17472
	ds_read_b128 v[100:103], v181 offset:21824
	ds_read_b128 v[108:111], v180 offset:128
	ds_read_b128 v[112:115], v181 offset:17536
	v_add_u32_e32 v192, v178, v228
	ds_read_b128 v[116:119], v181 offset:21888
	ds_read_b128 v[120:123], v180 offset:192
	s_waitcnt lgkmcnt(8)
	v_mfma_f32_16x16x32_bf16 v[88:91], v[84:87], v[88:91], 0
	s_add_u32 s98, s98, s100
	s_addc_u32 s99, s99, 0
	global_load_dword v251, v151, s[98:99]
	ds_read_b128 v[124:127], v181 offset:17600
	s_waitcnt lgkmcnt(8)
	v_mfma_f32_16x16x32_bf16 v[84:87], v[84:87], v[92:95], 0
	ds_read_b128 v[128:131], v181 offset:21952
	s_waitcnt lgkmcnt(7)
	v_mfma_f32_16x16x32_bf16 v[88:91], v[104:107], v[96:99], v[88:91]
	s_waitcnt lgkmcnt(6)
	v_mfma_f32_16x16x32_bf16 v[84:87], v[104:107], v[100:103], v[84:87]
	s_waitcnt lgkmcnt(4)
	v_mfma_f32_16x16x32_bf16 v[88:91], v[108:111], v[112:115], v[88:91]
	s_add_u32 s98, s98, s100
	s_addc_u32 s99, s99, 0
	global_load_dword v252, v151, s[98:99]
	s_waitcnt lgkmcnt(3)
	v_mfma_f32_16x16x32_bf16 v[84:87], v[108:111], v[116:119], v[84:87]
	s_waitcnt lgkmcnt(1)
	v_mfma_f32_16x16x32_bf16 v[88:91], v[120:123], v[124:127], v[88:91]
	s_waitcnt lgkmcnt(0)
	v_mfma_f32_16x16x32_bf16 v[84:87], v[120:123], v[128:131], v[84:87]
	s_nop 7
	ds_write2_b32 v202, v88, v84 offset1:16
	ds_write2_b32 v202, v89, v85 offset0:68 offset1:84
	ds_write2_b32 v202, v90, v86 offset0:136 offset1:152
	s_add_u32 s98, s98, s100
	s_addc_u32 s99, s99, 0
	global_load_dword v249, v151, s[98:99]
	ds_write2_b32 v202, v91, v87 offset0:204 offset1:220
	ds_read2_b64 v[92:95], v224 offset1:4
	ds_read2_b64 v[100:103], v225 offset1:4
	ds_read2_b64 v[108:111], v226 offset1:4
	ds_read2_b64 v[116:119], v227 offset1:4
	ds_read2_b64 v[124:127], v224 offset0:8 offset1:12
	ds_read2_b64 v[128:131], v225 offset0:8 offset1:12
	ds_read2_b64 v[132:135], v226 offset0:8 offset1:12
	ds_read2_b64 v[136:139], v227 offset0:8 offset1:12
	v_cvt_pk_bf16_f32 v84, v4, v5
	s_add_u32 s98, s98, 0x2000
	s_addc_u32 s99, s99, 0
	global_load_dword v248, v151, s[98:99]
	v_cvt_pk_bf16_f32 v85, v6, v7
	v_cvt_pk_bf16_f32 v86, v12, v13
	v_cvt_pk_bf16_f32 v87, v14, v15
	v_cvt_pk_bf16_f32 v88, v8, v9
	v_cvt_pk_bf16_f32 v89, v10, v11
	v_cvt_pk_bf16_f32 v90, v16, v17
	v_cvt_pk_bf16_f32 v91, v18, v19
	ds_read2_b64 v[140:143], v224 offset0:16 offset1:20
	s_waitcnt lgkmcnt(8)
	v_mfma_f32_16x16x32_bf16 v[96:99], v[92:95], v[84:87], 0
	s_add_u32 s98, s98, 0x2000
	s_addc_u32 s99, s99, 0
	global_load_dword v247, v151, s[98:99]
	v_mfma_f32_16x16x32_bf16 v[92:95], v[92:95], v[88:91], 0
	ds_read2_b64 v[144:147], v225 offset0:16 offset1:20
	s_waitcnt lgkmcnt(8)
	v_mfma_f32_16x16x32_bf16 v[104:107], v[100:103], v[84:87], 0
	v_mfma_f32_16x16x32_bf16 v[100:103], v[100:103], v[88:91], 0
	s_waitcnt lgkmcnt(7)
	v_mfma_f32_16x16x32_bf16 v[112:115], v[108:111], v[84:87], 0
	v_mfma_f32_16x16x32_bf16 v[108:111], v[108:111], v[88:91], 0
	s_waitcnt lgkmcnt(6)
	v_mfma_f32_16x16x32_bf16 v[84:87], v[116:119], v[84:87], 0
	s_add_u32 s98, s98, 0x2000
	s_addc_u32 s99, s99, 0
	global_load_dword v246, v151, s[98:99]
	v_mfma_f32_16x16x32_bf16 v[88:91], v[116:119], v[88:91], 0
	v_cvt_pk_bf16_f32 v116, v20, v21
	v_cvt_pk_bf16_f32 v117, v22, v23
	v_cvt_pk_bf16_f32 v118, v28, v29
	v_cvt_pk_bf16_f32 v119, v30, v31
	v_cvt_pk_bf16_f32 v120, v24, v25
	v_cvt_pk_bf16_f32 v121, v26, v27
	v_cvt_pk_bf16_f32 v122, v32, v33
	v_cvt_pk_bf16_f32 v123, v34, v35
	s_waitcnt lgkmcnt(5)
	s_add_u32 s98, s98, 0x2000
	s_addc_u32 s99, s99, 0
	global_load_dword v245, v151, s[98:99]
	v_mfma_f32_16x16x32_bf16 v[96:99], v[124:127], v[116:119], v[96:99]
	v_mfma_f32_16x16x32_bf16 v[92:95], v[124:127], v[120:123], v[92:95]
	ds_read2_b64 v[124:127], v226 offset0:16 offset1:20
	s_waitcnt lgkmcnt(5)
	v_mfma_f32_16x16x32_bf16 v[104:107], v[128:131], v[116:119], v[104:107]
	v_mfma_f32_16x16x32_bf16 v[100:103], v[128:131], v[120:123], v[100:103]
	s_waitcnt lgkmcnt(4)
	v_mfma_f32_16x16x32_bf16 v[112:115], v[132:135], v[116:119], v[112:115]
	v_mfma_f32_16x16x32_bf16 v[108:111], v[132:135], v[120:123], v[108:111]
	s_waitcnt lgkmcnt(3)
	s_add_u32 s98, s98, 0x2000
	s_addc_u32 s99, s99, 0
	global_load_dword v244, v151, s[98:99]
	v_mfma_f32_16x16x32_bf16 v[84:87], v[136:139], v[116:119], v[84:87]
	v_cvt_pk_bf16_f32 v116, v36, v37
	v_cvt_pk_bf16_f32 v117, v38, v39
	v_cvt_pk_bf16_f32 v118, v44, v45
	v_mfma_f32_16x16x32_bf16 v[88:91], v[136:139], v[120:123], v[88:91]
	v_cvt_pk_bf16_f32 v119, v46, v47
	v_cvt_pk_bf16_f32 v120, v40, v41
	v_cvt_pk_bf16_f32 v121, v42, v43
	v_cvt_pk_bf16_f32 v122, v48, v49
	v_cvt_pk_bf16_f32 v123, v50, v51
	s_add_u32 s98, s98, 0x2000
	s_addc_u32 s99, s99, 0
	global_load_dword v243, v151, s[98:99]
	s_waitcnt lgkmcnt(2)
	v_mfma_f32_16x16x32_bf16 v[96:99], v[140:143], v[116:119], v[96:99]
	v_mfma_f32_16x16x32_bf16 v[92:95], v[140:143], v[120:123], v[92:95]
	s_waitcnt lgkmcnt(1)
	v_mfma_f32_16x16x32_bf16 v[104:107], v[144:147], v[116:119], v[104:107]
	v_mfma_f32_16x16x32_bf16 v[100:103], v[144:147], v[120:123], v[100:103]
	s_waitcnt lgkmcnt(0)
	v_mfma_f32_16x16x32_bf16 v[112:115], v[124:127], v[116:119], v[112:115]
	v_mfma_f32_16x16x32_bf16 v[108:111], v[124:127], v[120:123], v[108:111]
	ds_read2_b64 v[124:127], v227 offset0:16 offset1:20
	s_add_u32 s98, s98, 0x2000
	s_addc_u32 s99, s99, 0
	global_load_dword v242, v151, s[98:99]
	s_waitcnt lgkmcnt(0)
	v_mfma_f32_16x16x32_bf16 v[84:87], v[124:127], v[116:119], v[84:87]
	v_mfma_f32_16x16x32_bf16 v[116:119], v[124:127], v[120:123], v[88:91]
	ds_read2_b64 v[124:127], v224 offset0:24 offset1:28
	s_nop 1
	v_cvt_pk_bf16_f32 v88, v52, v53
	v_cvt_pk_bf16_f32 v89, v54, v55
	v_cvt_pk_bf16_f32 v90, v60, v61
	v_cvt_pk_bf16_f32 v91, v62, v63
	v_cvt_pk_bf16_f32 v120, v56, v57
	s_add_u32 s98, s98, 0x2000
	s_addc_u32 s99, s99, 0
	global_load_dword v241, v151, s[98:99]
	v_cvt_pk_bf16_f32 v121, v58, v59
	v_cvt_pk_bf16_f32 v122, v64, v65
	v_cvt_pk_bf16_f32 v123, v66, v67
	s_waitcnt lgkmcnt(0)
	v_mfma_f32_16x16x32_bf16 v[128:131], v[124:127], v[88:91], v[96:99]
	v_mfma_f32_16x16x32_bf16 v[124:127], v[124:127], v[120:123], v[92:95]
	s_nop 2
	ds_read2_b64 v[92:95], v225 offset0:24 offset1:28
	s_nop 2
	s_waitcnt lgkmcnt(0)
	s_add_u32 s98, s98, 0x2000
	s_addc_u32 s99, s99, 0
	global_load_dword v240, v151, s[98:99]
	v_mfma_f32_16x16x32_bf16 v[104:107], v[92:95], v[88:91], v[104:107]
	v_mfma_f32_16x16x32_bf16 v[132:135], v[92:95], v[120:123], v[100:103]
	ds_read2_b64 v[92:95], v226 offset0:24 offset1:28
	s_waitcnt lgkmcnt(0)
	v_mfma_f32_16x16x32_bf16 v[100:103], v[92:95], v[88:91], v[112:115]
	v_mfma_f32_16x16x32_bf16 v[96:99], v[92:95], v[120:123], v[108:111]
	ds_read2_b64 v[92:95], v227 offset0:24 offset1:28
	s_waitcnt lgkmcnt(0)
	v_mfma_f32_16x16x32_bf16 v[88:91], v[92:95], v[88:91], v[84:87]
	v_mfma_f32_16x16x32_bf16 v[92:95], v[92:95], v[120:123], v[116:119]
	s_add_u32 s98, s98, 0x2000
	s_addc_u32 s99, s99, 0
	global_load_dword v239, v151, s[98:99]
	v_add_u32_e32 v120, s33, v156
	s_nop 0
	ds_read_b128 v[84:87], v120
	ds_read_b128 v[136:139], v120 offset:64
	ds_read_b128 v[140:143], v120 offset:128
	s_nop 0
	s_waitcnt lgkmcnt(2)
	v_mul_f32_e32 v2, 0x3fb8aa3b, v84
	v_mul_f32_e32 v84, 0x3fb8aa3b, v86
	v_exp_f32_e32 v108, v84
	s_add_u32 s98, s98, 0x2000
	s_addc_u32 s99, s99, 0
	global_load_dword v238, v151, s[98:99]
	v_mul_f32_e32 v84, 0x3fb8aa3b, v87
	v_exp_f32_e32 v109, v84
	v_mul_f32_e32 v3, 0x3fb8aa3b, v85
	v_exp_f32_e32 v2, v2
	v_exp_f32_e32 v3, v3
	v_pk_mul_f32 v[86:87], v[130:131], v[108:109]
	v_pk_mul_f32 v[118:119], v[126:127], v[108:109]
	v_pk_mul_f32 v[84:85], v[128:129], v[2:3]
	v_pk_mul_f32 v[116:117], v[124:125], v[2:3]
	s_waitcnt lgkmcnt(1)
	s_add_u32 s98, s98, 0x2000
	s_addc_u32 s99, s99, 0
	global_load_dword v237, v151, s[98:99]
	v_mul_f32_e32 v2, 0x3fb8aa3b, v136
	v_mul_f32_e32 v108, 0x3fb8aa3b, v138
	v_mul_f32_e32 v3, 0x3fb8aa3b, v137
	v_exp_f32_e32 v112, v108
	v_mul_f32_e32 v108, 0x3fb8aa3b, v139
	v_exp_f32_e32 v2, v2
	v_exp_f32_e32 v3, v3
	v_exp_f32_e32 v113, v108
	v_pk_mul_f32 v[108:109], v[104:105], v[2:3]
	v_pk_mul_f32 v[110:111], v[106:107], v[112:113]
	s_add_u32 s98, s98, 0x2000
	s_addc_u32 s99, s99, 0
	global_load_dword v236, v151, s[98:99]
	v_pk_mul_f32 v[114:115], v[134:135], v[112:113]
	v_pk_mul_f32 v[112:113], v[132:133], v[2:3]
	s_waitcnt lgkmcnt(0)
	v_mul_f32_e32 v2, 0x3fb8aa3b, v140
	v_mul_f32_e32 v3, 0x3fb8aa3b, v141
	v_mul_f32_e32 v104, 0x3fb8aa3b, v142
	v_mul_f32_e32 v105, 0x3fb8aa3b, v143
	v_exp_f32_e32 v2, v2
	v_exp_f32_e32 v3, v3
	v_exp_f32_e32 v104, v104
	v_exp_f32_e32 v105, v105
	v_pk_mul_f32 v[100:101], v[100:101], v[2:3]
	v_pk_mul_f32 v[102:103], v[102:103], v[104:105]
	v_pk_mul_f32 v[106:107], v[98:99], v[104:105]
	v_pk_mul_f32 v[104:105], v[96:97], v[2:3]
	ds_read_b128 v[96:99], v120 offset:192
	s_waitcnt vmcnt(21)
	ds_write_b128 v230, v[76:79]
	s_waitcnt vmcnt(20)
	ds_write_b128 v230, v[80:83] offset:128
	s_waitcnt vmcnt(19)
	ds_write_b128 v230, v[72:75] offset:256
	s_waitcnt vmcnt(18)
	ds_write_b128 v230, v[68:71] offset:384
	s_waitcnt lgkmcnt(0)
	s_barrier
	v_mul_f32_e32 v2, 0x3fb8aa3b, v96
	v_mul_f32_e32 v3, 0x3fb8aa3b, v97
	v_mul_f32_e32 v96, 0x3fb8aa3b, v98
	v_mul_f32_e32 v97, 0x3fb8aa3b, v99
	v_exp_f32_e32 v2, v2
	v_exp_f32_e32 v3, v3
	v_exp_f32_e32 v96, v96
	v_exp_f32_e32 v97, v97
	v_pk_mul_f32 v[88:89], v[88:89], v[2:3]
	v_pk_mul_f32 v[90:91], v[90:91], v[96:97]
	v_pk_mul_f32 v[98:99], v[94:95], v[96:97]
	v_pk_mul_f32 v[96:97], v[92:93], v[2:3]
	v_mov_b32_e32 v2, s33
	ds_read_b32 v253, v2 offset:252
	ds_read_b128 v[148:151], v209
	ds_read_b128 v[140:143], v209 offset:16
	ds_read_b128 v[144:147], v201
	ds_read_b128 v[124:127], v201 offset:16
	ds_read_b128 v[120:123], v192 offset:53248
	s_waitcnt lgkmcnt(5)
	v_mul_f32_e32 v2, 0x3fb8aa3b, v253
	v_exp_f32_e32 v2, v2
	s_nop 0
	v_pk_mul_f32 v[6:7], v[6:7], v[2:3] op_sel_hi:[1,0]
	v_pk_mul_f32 v[4:5], v[4:5], v[2:3] op_sel_hi:[1,0]
	v_pk_mul_f32 v[74:75], v[10:11], v[2:3] op_sel_hi:[1,0]
	v_pk_mul_f32 v[72:73], v[8:9], v[2:3] op_sel_hi:[1,0]
	v_pk_mul_f32 v[10:11], v[14:15], v[2:3] op_sel_hi:[1,0]
	v_pk_mul_f32 v[8:9], v[12:13], v[2:3] op_sel_hi:[1,0]
	v_pk_mul_f32 v[18:19], v[18:19], v[2:3] op_sel_hi:[1,0]
	v_pk_mul_f32 v[16:17], v[16:17], v[2:3] op_sel_hi:[1,0]
	v_pk_mul_f32 v[14:15], v[22:23], v[2:3] op_sel_hi:[1,0]
	v_pk_mul_f32 v[12:13], v[20:21], v[2:3] op_sel_hi:[1,0]
	v_pk_mul_f32 v[26:27], v[26:27], v[2:3] op_sel_hi:[1,0]
	v_pk_mul_f32 v[24:25], v[24:25], v[2:3] op_sel_hi:[1,0]
	v_pk_mul_f32 v[22:23], v[30:31], v[2:3] op_sel_hi:[1,0]
	v_pk_mul_f32 v[20:21], v[28:29], v[2:3] op_sel_hi:[1,0]
	v_pk_mul_f32 v[34:35], v[34:35], v[2:3] op_sel_hi:[1,0]
	v_pk_mul_f32 v[32:33], v[32:33], v[2:3] op_sel_hi:[1,0]
	v_pk_mul_f32 v[30:31], v[38:39], v[2:3] op_sel_hi:[1,0]
	v_pk_mul_f32 v[28:29], v[36:37], v[2:3] op_sel_hi:[1,0]
	v_pk_mul_f32 v[42:43], v[42:43], v[2:3] op_sel_hi:[1,0]
	v_pk_mul_f32 v[40:41], v[40:41], v[2:3] op_sel_hi:[1,0]
	v_pk_mul_f32 v[38:39], v[46:47], v[2:3] op_sel_hi:[1,0]
	v_pk_mul_f32 v[36:37], v[44:45], v[2:3] op_sel_hi:[1,0]
	v_pk_mul_f32 v[50:51], v[50:51], v[2:3] op_sel_hi:[1,0]
	v_pk_mul_f32 v[48:49], v[48:49], v[2:3] op_sel_hi:[1,0]
	v_pk_mul_f32 v[46:47], v[54:55], v[2:3] op_sel_hi:[1,0]
	v_pk_mul_f32 v[44:45], v[52:53], v[2:3] op_sel_hi:[1,0]
	v_pk_mul_f32 v[58:59], v[58:59], v[2:3] op_sel_hi:[1,0]
	v_pk_mul_f32 v[56:57], v[56:57], v[2:3] op_sel_hi:[1,0]
	v_pk_mul_f32 v[54:55], v[62:63], v[2:3] op_sel_hi:[1,0]
	v_pk_mul_f32 v[52:53], v[60:61], v[2:3] op_sel_hi:[1,0]
	v_pk_mul_f32 v[62:63], v[66:67], v[2:3] op_sel_hi:[1,0]
	v_pk_mul_f32 v[60:61], v[64:65], v[2:3] op_sel_hi:[1,0]
	ds_read_b128 v[64:67], v192 offset:55552
	ds_read_b32 v2, v229
	ds_read_b128 v[68:71], v232
	ds_read_b128 v[76:79], v232 offset:16
	s_waitcnt lgkmcnt(2)
	v_sub_f32_e32 v3, v2, v148
	v_mul_f32_e32 v3, 0x3fb8aa3b, v3
	v_exp_f32_e32 v3, v3
	s_waitcnt lgkmcnt(1)
	v_mul_f32_e32 v3, v68, v3
	v_sub_f32_e32 v68, v2, v149
	v_mul_f32_e32 v68, 0x3fb8aa3b, v68
	v_exp_f32_e32 v68, v68
	v_mul_f32_e32 v3, v144, v3
	v_cndmask_b32_e64 v3, v3, 0, s[24:25]
	v_mul_f32_e32 v68, v69, v68
	v_sub_f32_e32 v69, v2, v150
	v_mul_f32_e32 v69, 0x3fb8aa3b, v69
	v_exp_f32_e32 v69, v69
	v_mul_f32_e32 v68, v145, v68
	v_cndmask_b32_e64 v68, 0, v68, s[26:27]
	ds_read_b32 v80, v229 offset:64
	ds_read_b128 v[128:131], v232 offset:4352
	ds_read_b128 v[132:135], v232 offset:4368
	v_cvt_pk_bf16_f32 v68, v3, v68
	v_mul_f32_e32 v69, v70, v69
	v_sub_f32_e32 v70, v2, v151
	v_mul_f32_e32 v70, 0x3fb8aa3b, v70
	v_exp_f32_e32 v70, v70
	v_mul_f32_e32 v69, v146, v69
	v_cndmask_b32_e64 v69, v69, 0, s[28:29]
	v_mul_f32_e32 v70, v71, v70
	v_sub_f32_e32 v71, v2, v140
	v_mul_f32_e32 v71, 0x3fb8aa3b, v71
	v_exp_f32_e32 v71, v71
	v_mul_f32_e32 v70, v147, v70
	v_cndmask_b32_e64 v70, v70, 0, s[30:31]
	v_cvt_pk_bf16_f32 v69, v69, v70
	s_waitcnt lgkmcnt(3)
	v_mul_f32_e32 v71, v76, v71
	v_sub_f32_e32 v76, v2, v141
	v_mul_f32_e32 v76, 0x3fb8aa3b, v76
	v_exp_f32_e32 v76, v76
	v_mul_f32_e32 v71, v124, v71
	v_cndmask_b32_e64 v71, v71, 0, s[34:35]
	v_mul_f32_e32 v76, v77, v76
	v_sub_f32_e32 v77, v2, v142
	v_sub_f32_e32 v2, v2, v143
	v_mul_f32_e32 v77, 0x3fb8aa3b, v77
	v_mul_f32_e32 v2, 0x3fb8aa3b, v2
	v_exp_f32_e32 v77, v77
	v_exp_f32_e32 v2, v2
	v_mul_f32_e32 v76, v125, v76
	v_cndmask_b32_e64 v76, v76, 0, s[36:37]
	v_mul_f32_e32 v77, v78, v77
	v_mul_f32_e32 v2, v79, v2
	v_mul_f32_e32 v77, v126, v77
	v_mul_f32_e32 v2, v127, v2
	v_cndmask_b32_e64 v77, v77, 0, s[38:39]
	v_cndmask_b32_e64 v2, v2, 0, s[40:41]
	v_cvt_pk_bf16_f32 v70, v71, v76
	v_cvt_pk_bf16_f32 v71, v77, v2
	s_nop 0
	s_nop 0
	v_mfma_f32_16x16x32_bf16 v[92:95], v[68:71], v[120:123], v[84:87]
	v_mfma_f32_16x16x32_bf16 v[84:87], v[68:71], v[64:67], v[116:119]
	s_waitcnt lgkmcnt(2)
	v_sub_f32_e32 v3, v80, v148
	v_mul_f32_e32 v3, 0x3fb8aa3b, v3
	v_exp_f32_e32 v3, v3
	s_waitcnt lgkmcnt(1)
	v_mul_f32_e32 v3, v128, v3
	v_sub_f32_e32 v68, v80, v149
	v_mul_f32_e32 v68, 0x3fb8aa3b, v68
	v_exp_f32_e32 v68, v68
	v_mul_f32_e32 v3, v144, v3
	v_cndmask_b32_e64 v3, v3, 0, s[42:43]
	v_mul_f32_e32 v68, v129, v68
	v_sub_f32_e32 v69, v80, v150
	v_mul_f32_e32 v69, 0x3fb8aa3b, v69
	v_exp_f32_e32 v69, v69
	v_mul_f32_e32 v68, v145, v68
	ds_read_b32 v116, v229 offset:128
	ds_read_b128 v[136:139], v232 offset:8704
	v_cndmask_b32_e64 v68, 0, v68, s[44:45]
	v_cvt_pk_bf16_f32 v68, v3, v68
	v_mul_f32_e32 v69, v130, v69
	v_sub_f32_e32 v70, v80, v151
	v_mul_f32_e32 v70, 0x3fb8aa3b, v70
	v_exp_f32_e32 v70, v70
	v_mul_f32_e32 v69, v146, v69
	v_cndmask_b32_e64 v69, v69, 0, s[46:47]
	v_mul_f32_e32 v70, v131, v70
	v_sub_f32_e32 v71, v80, v140
	v_mul_f32_e32 v71, 0x3fb8aa3b, v71
	v_exp_f32_e32 v71, v71
	v_mul_f32_e32 v70, v147, v70
	v_cndmask_b32_e64 v70, v70, 0, s[48:49]
	v_cvt_pk_bf16_f32 v69, v69, v70
	s_waitcnt lgkmcnt(2)
	v_mul_f32_e32 v71, v132, v71
	v_sub_f32_e32 v76, v80, v141
	v_mul_f32_e32 v76, 0x3fb8aa3b, v76
	v_exp_f32_e32 v76, v76
	v_mul_f32_e32 v71, v124, v71
	v_cndmask_b32_e64 v71, v71, 0, s[50:51]
	v_mul_f32_e32 v76, v133, v76
	v_sub_f32_e32 v77, v80, v142
	v_sub_f32_e32 v2, v80, v143
	v_mul_f32_e32 v77, 0x3fb8aa3b, v77
	v_mul_f32_e32 v2, 0x3fb8aa3b, v2
	v_exp_f32_e32 v77, v77
	v_exp_f32_e32 v2, v2
	v_mul_f32_e32 v76, v125, v76
	v_cndmask_b32_e64 v76, v76, 0, s[52:53]
	v_mul_f32_e32 v77, v134, v77
	v_mul_f32_e32 v2, v135, v2
	v_mul_f32_e32 v77, v126, v77
	v_mul_f32_e32 v2, v127, v2
	v_cndmask_b32_e64 v77, v77, 0, s[54:55]
	v_cndmask_b32_e64 v2, v2, 0, s[56:57]
	v_cvt_pk_bf16_f32 v70, v71, v76
	v_cvt_pk_bf16_f32 v71, v77, v2
	s_nop 0
	s_nop 0
	v_mfma_f32_16x16x32_bf16 v[76:79], v[68:71], v[120:123], v[108:111]
	s_nop 2
	ds_read_b128 v[108:111], v232 offset:8720
	s_nop 0
	s_waitcnt lgkmcnt(2)
	v_sub_f32_e32 v3, v116, v148
	v_mul_f32_e32 v3, 0x3fb8aa3b, v3
	v_exp_f32_e32 v3, v3
	v_mfma_f32_16x16x32_bf16 v[68:71], v[68:71], v[64:67], v[112:115]
	s_waitcnt lgkmcnt(1)
	v_mul_f32_e32 v3, v136, v3
	v_sub_f32_e32 v80, v116, v149
	v_mul_f32_e32 v80, 0x3fb8aa3b, v80
	v_exp_f32_e32 v80, v80
	ds_read_b32 v112, v229 offset:192
	ds_read_b128 v[128:131], v232 offset:13056
	v_mul_f32_e32 v3, v144, v3
	v_mul_f32_e32 v80, v137, v80
	v_sub_f32_e32 v81, v116, v150
	v_mul_f32_e32 v81, 0x3fb8aa3b, v81
	v_exp_f32_e32 v81, v81
	v_mul_f32_e32 v80, v145, v80
	v_cvt_pk_bf16_f32 v80, v3, v80
	v_mul_f32_e32 v81, v138, v81
	v_sub_f32_e32 v82, v116, v151
	v_mul_f32_e32 v82, 0x3fb8aa3b, v82
	v_exp_f32_e32 v82, v82
	v_mul_f32_e32 v81, v146, v81
	v_mul_f32_e32 v82, v139, v82
	v_sub_f32_e32 v83, v116, v140
	v_mul_f32_e32 v83, 0x3fb8aa3b, v83
	v_exp_f32_e32 v83, v83
	v_mul_f32_e32 v82, v147, v82
	v_cvt_pk_bf16_f32 v81, v81, v82
	s_waitcnt lgkmcnt(2)
	v_mul_f32_e32 v83, v108, v83
	v_sub_f32_e32 v108, v116, v141
	v_mul_f32_e32 v108, 0x3fb8aa3b, v108
	v_exp_f32_e32 v108, v108
	v_mul_f32_e32 v83, v124, v83
	v_mul_f32_e32 v108, v109, v108
	v_sub_f32_e32 v109, v116, v142
	v_sub_f32_e32 v2, v116, v143
	v_mul_f32_e32 v109, 0x3fb8aa3b, v109
	v_mul_f32_e32 v2, 0x3fb8aa3b, v2
	v_exp_f32_e32 v109, v109
	v_exp_f32_e32 v2, v2
	v_mul_f32_e32 v108, v125, v108
	v_cvt_pk_bf16_f32 v82, v83, v108
	v_mul_f32_e32 v109, v110, v109
	v_mul_f32_e32 v2, v111, v2
	v_mul_f32_e32 v109, v126, v109
	v_mul_f32_e32 v2, v127, v2
	v_cvt_pk_bf16_f32 v83, v109, v2
	s_nop 0
	s_nop 0
	v_mfma_f32_16x16x32_bf16 v[132:135], v[80:83], v[120:123], v[100:103]
	s_nop 2
	ds_read_b128 v[100:103], v232 offset:13072
	v_mfma_f32_16x16x32_bf16 v[136:139], v[80:83], v[64:67], v[104:107]
	s_waitcnt lgkmcnt(2)
	v_sub_f32_e32 v3, v112, v148
	v_mul_f32_e32 v3, 0x3fb8aa3b, v3
	v_exp_f32_e32 v3, v3
	s_waitcnt lgkmcnt(1)
	v_mul_f32_e32 v3, v128, v3
	v_sub_f32_e32 v80, v112, v149
	v_mul_f32_e32 v80, 0x3fb8aa3b, v80
	v_exp_f32_e32 v80, v80
	v_mul_f32_e32 v3, v144, v3
	v_mul_f32_e32 v80, v129, v80
	v_sub_f32_e32 v81, v112, v150
	v_mul_f32_e32 v81, 0x3fb8aa3b, v81
	v_exp_f32_e32 v81, v81
	v_mul_f32_e32 v80, v145, v80
	v_mul_f32_e32 v81, v130, v81
	v_sub_f32_e32 v82, v112, v151
	v_mul_f32_e32 v82, 0x3fb8aa3b, v82
	v_exp_f32_e32 v82, v82
	v_mul_f32_e32 v81, v146, v81
	v_mul_f32_e32 v82, v131, v82
	v_sub_f32_e32 v83, v112, v140
	v_mul_f32_e32 v83, 0x3fb8aa3b, v83
	v_exp_f32_e32 v83, v83
	v_mul_f32_e32 v82, v147, v82
	s_waitcnt lgkmcnt(0)
	v_mul_f32_e32 v83, v100, v83
	v_sub_f32_e32 v100, v112, v141
	v_mul_f32_e32 v100, 0x3fb8aa3b, v100
	v_exp_f32_e32 v100, v100
	v_mul_f32_e32 v83, v124, v83
	v_mul_f32_e32 v100, v101, v100
	v_mul_f32_e32 v104, v125, v100
	v_sub_f32_e32 v100, v112, v142
	v_sub_f32_e32 v2, v112, v143
	v_mul_f32_e32 v100, 0x3fb8aa3b, v100
	v_mul_f32_e32 v2, 0x3fb8aa3b, v2
	v_exp_f32_e32 v100, v100
	v_exp_f32_e32 v2, v2
	v_mul_f32_e32 v100, v102, v100
	v_mul_f32_e32 v2, v103, v2
	v_mul_f32_e32 v105, v126, v100
	v_mul_f32_e32 v2, v127, v2
	v_cvt_pk_bf16_f32 v100, v3, v80
	v_cvt_pk_bf16_f32 v101, v81, v82
	v_cvt_pk_bf16_f32 v102, v83, v104
	v_cvt_pk_bf16_f32 v103, v105, v2
	v_sub_f32_e32 v2, v253, v148
	s_nop 0
	v_mfma_f32_16x16x32_bf16 v[80:83], v[100:103], v[120:123], v[88:91]
	v_sub_f32_e32 v3, v253, v149
	v_mul_f32_e32 v2, 0x3fb8aa3b, v2
	v_mul_f32_e32 v3, 0x3fb8aa3b, v3
	v_sub_f32_e32 v88, v253, v150
	v_mul_f32_e32 v88, 0x3fb8aa3b, v88
	v_exp_f32_e32 v88, v88
	v_mfma_f32_16x16x32_bf16 v[128:131], v[100:103], v[64:67], v[96:99]
	v_exp_f32_e32 v2, v2
	v_exp_f32_e32 v3, v3
	v_and_b32_e32 v89, 0xffff0000, v120
	v_mul_f32_e32 v96, v146, v88
	v_sub_f32_e32 v88, v253, v151
	v_mul_f32_e32 v88, 0x3fb8aa3b, v88
	v_exp_f32_e32 v88, v88
	v_mul_f32_e32 v2, v144, v2
	v_mul_f32_e32 v3, v145, v3
	v_lshlrev_b32_e32 v90, 16, v121
	v_mul_f32_e32 v97, v147, v88
	v_sub_f32_e32 v88, v253, v140
	v_mul_f32_e32 v88, 0x3fb8aa3b, v88
	v_exp_f32_e32 v88, v88
	v_lshlrev_b32_e32 v102, 16, v122
	v_mul_f32_e32 v89, v3, v89
	v_mul_f32_e32 v90, v96, v90
	v_mul_f32_e32 v98, v124, v88
	v_sub_f32_e32 v88, v253, v141
	v_mul_f32_e32 v88, 0x3fb8aa3b, v88
	v_exp_f32_e32 v88, v88
	v_and_b32_e32 v91, 0xffff0000, v121
	v_mul_f32_e32 v102, v98, v102
	v_and_b32_e32 v103, 0xffff0000, v122
	v_mul_f32_e32 v99, v125, v88
	ds_read_b128 v[106:109], v233 offset:34816
	v_sub_f32_e32 v88, v253, v142
	v_mul_f32_e32 v88, 0x3fb8aa3b, v88
	ds_read_b128 v[110:113], v233 offset:37120
	v_exp_f32_e32 v88, v88
	v_mul_f32_e32 v91, v97, v91
	ds_read_b128 v[114:117], v233 offset:39424
	v_mul_f32_e32 v103, v99, v103
	v_lshlrev_b32_e32 v104, 16, v123
	ds_read_b128 v[144:147], v233 offset:41728
	v_mul_f32_e32 v100, v126, v88
	v_sub_f32_e32 v88, v253, v143
	ds_read_b128 v[148:151], v233 offset:44032
	v_mul_f32_e32 v88, 0x3fb8aa3b, v88
	v_exp_f32_e32 v88, v88
	v_and_b32_e32 v105, 0xffff0000, v123
	v_mul_f32_e32 v104, v100, v104
	v_mul_f32_e32 v101, v127, v88
	v_lshlrev_b32_e32 v88, 16, v120
	v_mul_f32_e32 v88, v2, v88
	v_cvt_pk_bf16_f32 v88, v88, v89
	v_cvt_pk_bf16_f32 v89, v90, v91
	v_cvt_pk_bf16_f32 v90, v102, v103
	v_lshlrev_b32_e32 v102, 16, v64
	v_and_b32_e32 v64, 0xffff0000, v64
	v_mul_f32_e32 v3, v3, v64
	v_lshlrev_b32_e32 v64, 16, v65
	v_mul_f32_e32 v64, v96, v64
	v_lshlrev_b32_e32 v96, 16, v66
	v_and_b32_e32 v65, 0xffff0000, v65
	v_mul_f32_e32 v98, v98, v96
	v_and_b32_e32 v66, 0xffff0000, v66
	v_lshlrev_b32_e32 v96, 16, v67
	v_and_b32_e32 v67, 0xffff0000, v67
	v_mul_f32_e32 v65, v97, v65
	v_mul_f32_e32 v66, v99, v66
	v_mul_f32_e32 v99, v100, v96
	v_mul_f32_e32 v67, v101, v67
	v_mul_f32_e32 v105, v101, v105
	v_cvt_pk_bf16_f32 v91, v104, v105
	v_mul_f32_e32 v2, v2, v102
	v_cvt_pk_bf16_f32 v96, v2, v3
	v_cvt_pk_bf16_f32 v97, v64, v65
	v_cvt_pk_bf16_f32 v98, v98, v66
	v_cvt_pk_bf16_f32 v99, v99, v67
	s_waitcnt lgkmcnt(4)
	v_mfma_f32_16x16x32_bf16 v[2:5], v[106:109], v[88:91], v[4:7]
	v_mfma_f32_16x16x32_bf16 v[140:143], v[106:109], v[96:99], v[72:75]
	s_waitcnt lgkmcnt(3)
	v_mfma_f32_16x16x32_bf16 v[120:123], v[110:113], v[88:91], v[8:11]
	s_nop 2
	ds_read_b128 v[6:9], v233 offset:46336
	s_nop 2
	s_waitcnt lgkmcnt(3)
	v_mfma_f32_16x16x32_bf16 v[124:127], v[114:117], v[88:91], v[12:15]
	v_mfma_f32_16x16x32_bf16 v[24:27], v[114:117], v[96:99], v[24:27]
	s_waitcnt lgkmcnt(2)
	v_mfma_f32_16x16x32_bf16 v[116:119], v[144:147], v[88:91], v[20:23]
	v_mfma_f32_16x16x32_bf16 v[32:35], v[144:147], v[96:99], v[32:35]
	v_mfma_f32_16x16x32_bf16 v[16:19], v[110:113], v[96:99], v[16:19]
	s_waitcnt lgkmcnt(1)
	v_mfma_f32_16x16x32_bf16 v[64:67], v[148:151], v[88:91], v[28:31]
	v_mfma_f32_16x16x32_bf16 v[40:43], v[148:151], v[96:99], v[40:43]
	s_waitcnt lgkmcnt(0)
	v_mfma_f32_16x16x32_bf16 v[100:103], v[6:9], v[88:91], v[36:39]
	v_mfma_f32_16x16x32_bf16 v[48:51], v[6:9], v[96:99], v[48:51]
	ds_read_b128 v[6:9], v233 offset:48640
	s_waitcnt lgkmcnt(0)
	v_mfma_f32_16x16x32_bf16 v[104:107], v[6:9], v[88:91], v[44:47]
	v_mfma_f32_16x16x32_bf16 v[56:59], v[6:9], v[96:99], v[56:59]
	ds_read_b128 v[6:9], v233 offset:50944
	s_nop 0
	ds_read_b128 v[44:47], v209 offset:128
	ds_read_b128 v[28:31], v209 offset:144
	ds_read_b128 v[36:39], v201 offset:128
	ds_read_b128 v[20:23], v201 offset:144
	ds_read_b128 v[10:13], v192 offset:53312
	s_waitcnt lgkmcnt(5)
	v_mfma_f32_16x16x32_bf16 v[108:111], v[6:9], v[88:91], v[52:55]
	v_mfma_f32_16x16x32_bf16 v[112:115], v[6:9], v[96:99], v[60:63]
	ds_read_b128 v[6:9], v192 offset:55616
	ds_read_b32 v14, v229 offset:128
	ds_read_b128 v[52:55], v232 offset:8832
	ds_read_b128 v[60:63], v232 offset:8848
	s_waitcnt lgkmcnt(2)
	v_sub_f32_e32 v15, v14, v44
	v_mul_f32_e32 v15, 0x3fb8aa3b, v15
	v_exp_f32_e32 v15, v15
	s_waitcnt lgkmcnt(1)
	v_mul_f32_e32 v15, v52, v15
	v_sub_f32_e32 v52, v14, v45
	v_mul_f32_e32 v52, 0x3fb8aa3b, v52
	v_exp_f32_e32 v52, v52
	v_mul_f32_e32 v15, v36, v15
	v_cndmask_b32_e64 v15, v15, 0, s[24:25]
	v_mul_f32_e32 v52, v53, v52
	v_sub_f32_e32 v53, v14, v46
	v_mul_f32_e32 v53, 0x3fb8aa3b, v53
	v_exp_f32_e32 v53, v53
	v_mul_f32_e32 v52, v37, v52
	v_cndmask_b32_e64 v52, v52, 0, s[58:59]
	ds_read_b32 v72, v229 offset:192
	ds_read_b128 v[144:147], v232 offset:13184
	ds_read_b128 v[148:151], v232 offset:13200
	v_cvt_pk_bf16_f32 v52, v15, v52
	v_mul_f32_e32 v53, v54, v53
	v_sub_f32_e32 v54, v14, v47
	v_mul_f32_e32 v54, 0x3fb8aa3b, v54
	v_exp_f32_e32 v54, v54
	v_mul_f32_e32 v53, v38, v53
	v_cndmask_b32_e64 v53, v53, 0, s[60:61]
	v_mul_f32_e32 v54, v55, v54
	v_sub_f32_e32 v55, v14, v28
	v_mul_f32_e32 v55, 0x3fb8aa3b, v55
	v_exp_f32_e32 v55, v55
	v_mul_f32_e32 v54, v39, v54
	v_cndmask_b32_e64 v54, v54, 0, s[62:63]
	v_cvt_pk_bf16_f32 v53, v53, v54
	s_waitcnt lgkmcnt(3)
	v_mul_f32_e32 v55, v60, v55
	v_sub_f32_e32 v60, v14, v29
	v_mul_f32_e32 v60, 0x3fb8aa3b, v60
	v_exp_f32_e32 v60, v60
	v_mul_f32_e32 v55, v20, v55
	v_cndmask_b32_e64 v55, v55, 0, s[64:65]
	v_mul_f32_e32 v60, v61, v60
	v_sub_f32_e32 v61, v14, v30
	v_sub_f32_e32 v14, v14, v31
	v_mul_f32_e32 v61, 0x3fb8aa3b, v61
	v_mul_f32_e32 v14, 0x3fb8aa3b, v14
	v_exp_f32_e32 v61, v61
	v_exp_f32_e32 v14, v14
	v_mul_f32_e32 v60, v21, v60
	v_cndmask_b32_e64 v60, v60, 0, s[66:67]
	v_mul_f32_e32 v61, v62, v61
	v_mul_f32_e32 v14, v63, v14
	v_mul_f32_e32 v61, v22, v61
	v_mul_f32_e32 v14, v23, v14
	v_cndmask_b32_e64 v61, v61, 0, s[68:69]
	v_cndmask_b32_e64 v14, v14, 0, s[70:71]
	v_cvt_pk_bf16_f32 v54, v55, v60
	v_cvt_pk_bf16_f32 v55, v61, v14
	s_nop 0
	s_nop 0
	v_mfma_f32_16x16x32_bf16 v[96:99], v[52:55], v[10:13], v[132:135]
	v_mfma_f32_16x16x32_bf16 v[88:91], v[52:55], v[6:9], v[136:139]
	s_waitcnt lgkmcnt(2)
	v_sub_f32_e32 v15, v72, v44
	v_mul_f32_e32 v15, 0x3fb8aa3b, v15
	v_exp_f32_e32 v15, v15
	s_waitcnt lgkmcnt(1)
	v_mul_f32_e32 v15, v144, v15
	v_sub_f32_e32 v52, v72, v45
	v_mul_f32_e32 v52, 0x3fb8aa3b, v52
	v_exp_f32_e32 v52, v52
	v_mul_f32_e32 v15, v36, v15
	v_cndmask_b32_e64 v15, v15, 0, s[72:73]
	v_mul_f32_e32 v52, v145, v52
	v_sub_f32_e32 v53, v72, v46
	v_mul_f32_e32 v53, 0x3fb8aa3b, v53
	v_exp_f32_e32 v53, v53
	v_mul_f32_e32 v52, v37, v52
	v_cndmask_b32_e64 v52, v52, 0, s[74:75]
	v_cvt_pk_bf16_f32 v52, v15, v52
	v_mul_f32_e32 v53, v146, v53
	v_sub_f32_e32 v54, v72, v47
	v_mul_f32_e32 v54, 0x3fb8aa3b, v54
	v_exp_f32_e32 v54, v54
	v_mul_f32_e32 v53, v38, v53
	v_cndmask_b32_e64 v53, v53, 0, s[76:77]
	v_sub_f32_e32 v15, v253, v45
	v_mul_f32_e32 v54, v147, v54
	v_sub_f32_e32 v55, v72, v28
	v_mul_f32_e32 v55, 0x3fb8aa3b, v55
	v_exp_f32_e32 v55, v55
	v_sub_f32_e32 v28, v253, v28
	v_mul_f32_e32 v28, 0x3fb8aa3b, v28
	v_exp_f32_e32 v28, v28
	s_waitcnt lgkmcnt(0)
	v_mul_f32_e32 v55, v148, v55
	v_sub_f32_e32 v60, v72, v29
	v_mul_f32_e32 v60, 0x3fb8aa3b, v60
	v_exp_f32_e32 v60, v60
	v_mul_f32_e32 v55, v20, v55
	v_mul_f32_e32 v20, v20, v28
	v_sub_f32_e32 v28, v253, v29
	v_mul_f32_e32 v60, v149, v60
	v_sub_f32_e32 v61, v72, v30
	v_sub_f32_e32 v14, v72, v31
	v_mul_f32_e32 v14, 0x3fb8aa3b, v14
	v_mul_f32_e32 v61, 0x3fb8aa3b, v61
	v_exp_f32_e32 v14, v14
	v_exp_f32_e32 v61, v61
	v_mul_f32_e32 v28, 0x3fb8aa3b, v28
	v_exp_f32_e32 v28, v28
	v_mul_f32_e32 v14, v151, v14
	v_mul_f32_e32 v54, v39, v54
	v_mul_f32_e32 v61, v150, v61
	v_mul_f32_e32 v14, v23, v14
	v_cndmask_b32_e64 v54, v54, 0, s[78:79]
	v_cndmask_b32_e64 v55, v55, 0, s[80:81]
	v_mul_f32_e32 v60, v21, v60
	v_mul_f32_e32 v61, v22, v61
	v_cndmask_b32_e64 v14, v14, 0, s[86:87]
	v_mul_f32_e32 v21, v21, v28
	v_sub_f32_e32 v28, v253, v30
	v_cndmask_b32_e64 v60, v60, 0, s[82:83]
	v_cndmask_b32_e64 v61, v61, 0, s[84:85]
	v_cvt_pk_bf16_f32 v53, v53, v54
	v_cvt_pk_bf16_f32 v54, v55, v60
	v_cvt_pk_bf16_f32 v55, v61, v14
	v_sub_f32_e32 v14, v253, v44
	v_mul_f32_e32 v15, 0x3fb8aa3b, v15
	v_mul_f32_e32 v28, 0x3fb8aa3b, v28
	v_mul_f32_e32 v14, 0x3fb8aa3b, v14
	v_exp_f32_e32 v15, v15
	v_exp_f32_e32 v28, v28
	v_exp_f32_e32 v14, v14
	v_mfma_f32_16x16x32_bf16 v[80:83], v[52:55], v[10:13], v[80:83]
	v_mul_f32_e32 v15, v37, v15
	v_sub_f32_e32 v37, v253, v47
	v_mul_f32_e32 v22, v22, v28
	v_sub_f32_e32 v28, v253, v31
	v_mul_f32_e32 v14, v36, v14
	v_sub_f32_e32 v36, v253, v46
	v_mul_f32_e32 v37, 0x3fb8aa3b, v37
	v_mul_f32_e32 v28, 0x3fb8aa3b, v28
	v_mul_f32_e32 v36, 0x3fb8aa3b, v36
	v_exp_f32_e32 v37, v37
	v_exp_f32_e32 v28, v28
	v_exp_f32_e32 v36, v36
	v_lshlrev_b32_e32 v29, 16, v11
	v_mul_f32_e32 v37, v39, v37
	v_mul_f32_e32 v23, v23, v28
	v_lshlrev_b32_e32 v28, 16, v10
	ds_read_b128 v[132:135], v233 offset:34880
	ds_read_b128 v[136:139], v233 offset:37184
	ds_read_b128 v[144:147], v233 offset:39488
	ds_read_b128 v[148:151], v233 offset:41792
	ds_read_b128 v[44:47], v233 offset:44096
	v_and_b32_e32 v10, 0xffff0000, v10
	v_and_b32_e32 v11, 0xffff0000, v11
	v_lshlrev_b32_e32 v30, 16, v12
	v_and_b32_e32 v12, 0xffff0000, v12
	v_lshlrev_b32_e32 v31, 16, v13
	v_and_b32_e32 v13, 0xffff0000, v13
	v_mul_f32_e32 v36, v38, v36
	v_mul_f32_e32 v10, v15, v10
	v_mul_f32_e32 v11, v37, v11
	v_mul_f32_e32 v12, v21, v12
	v_mul_f32_e32 v13, v23, v13
	v_mfma_f32_16x16x32_bf16 v[72:75], v[52:55], v[6:9], v[128:131]
	ds_read_b128 v[52:55], v233 offset:46400
	v_mul_f32_e32 v28, v14, v28
	v_mul_f32_e32 v29, v36, v29
	v_mul_f32_e32 v30, v20, v30
	v_mul_f32_e32 v31, v22, v31
	v_cvt_pk_bf16_f32 v60, v28, v10
	v_cvt_pk_bf16_f32 v61, v29, v11
	v_cvt_pk_bf16_f32 v62, v30, v12
	v_cvt_pk_bf16_f32 v63, v31, v13
	v_lshlrev_b32_e32 v10, 16, v6
	v_lshlrev_b32_e32 v11, 16, v7
	v_lshlrev_b32_e32 v12, 16, v8
	v_and_b32_e32 v8, 0xffff0000, v8
	v_lshlrev_b32_e32 v13, 16, v9
	v_and_b32_e32 v9, 0xffff0000, v9
	v_mul_f32_e32 v10, v14, v10
	v_and_b32_e32 v6, 0xffff0000, v6
	v_mul_f32_e32 v11, v36, v11
	v_and_b32_e32 v7, 0xffff0000, v7
	v_mul_f32_e32 v8, v21, v8
	v_mul_f32_e32 v9, v23, v9
	v_mul_f32_e32 v6, v15, v6
	v_mul_f32_e32 v7, v37, v7
	v_mul_f32_e32 v12, v20, v12
	v_mul_f32_e32 v13, v22, v13
	v_cvt_pk_bf16_f32 v128, v10, v6
	v_cvt_pk_bf16_f32 v129, v11, v7
	v_cvt_pk_bf16_f32 v130, v12, v8
	v_cvt_pk_bf16_f32 v131, v13, v9
	s_waitcnt lgkmcnt(4)
	v_mfma_f32_16x16x32_bf16 v[12:15], v[136:139], v[60:63], v[120:123]
	v_mfma_f32_16x16x32_bf16 v[16:19], v[136:139], v[128:131], v[16:19]
	s_waitcnt lgkmcnt(3)
	v_mfma_f32_16x16x32_bf16 v[20:23], v[144:147], v[60:63], v[124:127]
	v_mfma_f32_16x16x32_bf16 v[24:27], v[144:147], v[128:131], v[24:27]
	s_waitcnt lgkmcnt(2)
	v_mfma_f32_16x16x32_bf16 v[28:31], v[148:151], v[60:63], v[116:119]
	v_mfma_f32_16x16x32_bf16 v[32:35], v[148:151], v[128:131], v[32:35]
	s_waitcnt lgkmcnt(1)
	v_mfma_f32_16x16x32_bf16 v[36:39], v[44:47], v[60:63], v[64:67]
	s_nop 2
	ds_read_b128 v[64:67], v233 offset:48704
	s_nop 2
	v_mfma_f32_16x16x32_bf16 v[4:7], v[132:135], v[60:63], v[2:5]
	s_nop 2
	ds_read_b64 v[2:3], v234 offset:53248
	ds_read_u16 v192, v235
	v_mfma_f32_16x16x32_bf16 v[40:43], v[44:47], v[128:131], v[40:43]
	s_nop 1
	s_waitcnt lgkmcnt(3)
	v_mfma_f32_16x16x32_bf16 v[44:47], v[52:55], v[60:63], v[100:103]
	s_nop 2
	ds_read_u16 v103, v235 offset:528
	v_mfma_f32_16x16x32_bf16 v[48:51], v[52:55], v[128:131], v[48:51]
	s_nop 1
	s_waitcnt lgkmcnt(2)
	v_lshlrev_b32_e32 v100, 16, v2
	v_mfma_f32_16x16x32_bf16 v[52:55], v[64:67], v[60:63], v[104:107]
	v_and_b32_e32 v101, 0xffff0000, v2
	s_waitcnt lgkmcnt(1)
	v_lshlrev_b32_e32 v102, 16, v192
	s_waitcnt lgkmcnt(0)
	v_lshlrev_b32_e32 v103, 16, v103
	v_mfma_f32_16x16x32_bf16 v[56:59], v[64:67], v[128:131], v[56:59]
	ds_read_b128 v[64:67], v233 offset:51008
	ds_read_u16 v116, v235 offset:1056
	ds_read_u16 v117, v235 offset:1584
	ds_read_b64 v[104:105], v234 offset:55552
	ds_read_u16 v106, v235 offset:32
	ds_read_u16 v107, v235 offset:560
	v_pk_fma_f32 v[92:93], v[154:155], v[100:101], v[92:93]
	v_pk_mul_f32 v[100:101], v[102:103], s[96:97] op_sel_hi:[1,0]
	v_lshlrev_b32_e32 v2, 16, v3
	v_exp_f32_e32 v100, v100
	v_exp_f32_e32 v101, v101
	v_and_b32_e32 v3, 0xffff0000, v3
	v_pk_fma_f32 v[2:3], v[154:155], v[2:3], v[94:95]
	v_mfma_f32_16x16x32_bf16 v[8:11], v[132:135], v[128:131], v[140:143]
	v_add_f32_e64 v100, v100, 1.0
	v_add_f32_e64 v101, v101, 1.0
	v_rcp_f32_e32 v100, v100
	v_rcp_f32_e32 v101, v101
	s_waitcnt lgkmcnt(5)
	v_mfma_f32_16x16x32_bf16 v[60:63], v[64:67], v[60:63], v[108:111]
	v_mul_f32_e64 v100, v100, v102
	v_mul_f32_e64 v101, v101, v103
	v_pk_mul_f32 v[92:93], v[92:93], v[100:101]
	v_mfma_f32_16x16x32_bf16 v[64:67], v[64:67], v[128:131], v[112:115]
	v_cvt_pk_bf16_f32 v102, v92, v93
	ds_write_b16 v235, v102
	ds_write_b16_d16_hi v235, v102 offset:528
	s_waitcnt lgkmcnt(6)
	v_lshlrev_b32_e32 v92, 16, v116
	s_waitcnt lgkmcnt(5)
	v_lshlrev_b32_e32 v93, 16, v117
	ds_read_u16 v108, v235 offset:1088
	ds_read_u16 v109, v235 offset:1616
	v_pk_mul_f32 v[94:95], v[92:93], s[96:97] op_sel_hi:[1,0]
	s_nop 0
	v_exp_f32_e32 v94, v94
	v_exp_f32_e32 v95, v95
	s_nop 0
	v_pk_add_f32 v[94:95], v[94:95], 1.0 op_sel_hi:[1,0]
	s_nop 0
	v_rcp_f32_e32 v94, v94
	v_rcp_f32_e32 v95, v95
	s_nop 0
	v_pk_mul_f32 v[92:93], v[94:95], v[92:93]
	s_nop 0
	v_pk_mul_f32 v[2:3], v[2:3], v[92:93]
	s_nop 0
	v_cvt_pk_bf16_f32 v103, v2, v3
	ds_write_b16 v235, v103 offset:1056
	ds_write_b16_d16_hi v235, v103 offset:1584
	s_waitcnt lgkmcnt(8)
	v_lshlrev_b32_e32 v92, 16, v104
	v_and_b32_e32 v93, 0xffff0000, v104
	s_waitcnt lgkmcnt(7)
	v_lshlrev_b32_e32 v94, 16, v106
	s_waitcnt lgkmcnt(6)
	v_lshlrev_b32_e32 v95, 16, v107
	v_pk_fma_f32 v[84:85], v[154:155], v[92:93], v[84:85]
	v_pk_mul_f32 v[92:93], v[94:95], s[96:97] op_sel_hi:[1,0]
	v_lshlrev_b32_e32 v2, 16, v105
	v_exp_f32_e32 v92, v92
	v_exp_f32_e32 v93, v93
	v_and_b32_e32 v3, 0xffff0000, v105
	v_pk_fma_f32 v[2:3], v[154:155], v[2:3], v[86:87]
	v_pk_add_f32 v[92:93], v[92:93], 1.0 op_sel_hi:[1,0]
	s_nop 0
	v_rcp_f32_e32 v92, v92
	v_rcp_f32_e32 v93, v93
	s_nop 0
	v_pk_mul_f32 v[92:93], v[92:93], v[94:95]
	s_nop 0
	v_pk_mul_f32 v[84:85], v[84:85], v[92:93]
	s_nop 0
	v_cvt_pk_bf16_f32 v92, v84, v85
	ds_write_b16 v235, v92 offset:32
	ds_write_b16_d16_hi v235, v92 offset:560
	s_waitcnt lgkmcnt(5)
	v_lshlrev_b32_e32 v84, 16, v108
	s_waitcnt lgkmcnt(4)
	v_lshlrev_b32_e32 v85, 16, v109
	v_pk_mul_f32 v[86:87], v[84:85], s[96:97] op_sel_hi:[1,0]
	s_nop 0
	v_exp_f32_e32 v86, v86
	v_exp_f32_e32 v87, v87
	s_nop 0
	v_pk_add_f32 v[86:87], v[86:87], 1.0 op_sel_hi:[1,0]
	s_nop 0
	v_rcp_f32_e32 v86, v86
	v_rcp_f32_e32 v87, v87
	s_nop 0
	v_pk_mul_f32 v[84:85], v[86:87], v[84:85]
	s_nop 0
	v_pk_mul_f32 v[2:3], v[2:3], v[84:85]
	v_lshlrev_b32_e32 v84, 16, v92
	v_cvt_pk_bf16_f32 v93, v2, v3
	ds_write_b16 v235, v93 offset:1088
	ds_write_b16_d16_hi v235, v93 offset:1616
	v_and_b32_e32 v85, 0xffff0000, v92
	v_lshlrev_b32_e32 v92, 16, v93
	v_and_b32_e32 v93, 0xffff0000, v93
	v_pk_mul_f32 v[84:85], v[84:85], v[84:85]
	v_and_b32_e32 v3, 0xffff0000, v102
	v_lshlrev_b32_e32 v86, 16, v103
	v_lshlrev_b32_e32 v2, 16, v102
	v_and_b32_e32 v87, 0xffff0000, v103
	v_pk_mul_f32 v[92:93], v[92:93], v[92:93]
	v_pk_fma_f32 v[2:3], v[2:3], v[2:3], v[84:85]
	v_pk_fma_f32 v[86:87], v[86:87], v[86:87], v[92:93]
	s_nop 0
	v_add_u32_e32 v102, s12, v156
	v_add_f32_dpp v2, v2, v2 quad_perm:[1,0,3,2] row_mask:0xf bank_mask:0xf
	v_add_f32_dpp v3, v3, v3 quad_perm:[1,0,3,2] row_mask:0xf bank_mask:0xf
	v_add_f32_dpp v86, v86, v86 quad_perm:[1,0,3,2] row_mask:0xf bank_mask:0xf
	v_add_f32_dpp v87, v87, v87 quad_perm:[1,0,3,2] row_mask:0xf bank_mask:0xf
	v_add_f32_dpp v2, v2, v2 quad_perm:[2,3,0,1] row_mask:0xf bank_mask:0xf
	v_add_f32_dpp v3, v3, v3 quad_perm:[2,3,0,1] row_mask:0xf bank_mask:0xf
	v_add_f32_dpp v86, v86, v86 quad_perm:[2,3,0,1] row_mask:0xf bank_mask:0xf
	v_add_f32_dpp v87, v87, v87 quad_perm:[2,3,0,1] row_mask:0xf bank_mask:0xf
	v_add_f32_dpp v2, v2, v2 row_half_mirror row_mask:0xf bank_mask:0xf
	v_add_f32_dpp v3, v3, v3 row_half_mirror row_mask:0xf bank_mask:0xf
	v_add_f32_dpp v86, v86, v86 row_half_mirror row_mask:0xf bank_mask:0xf
	v_add_f32_dpp v87, v87, v87 row_half_mirror row_mask:0xf bank_mask:0xf
	v_add_f32_dpp v84, v2, v2 row_mirror row_mask:0xf bank_mask:0xf
	v_add_f32_dpp v85, v3, v3 row_mirror row_mask:0xf bank_mask:0xf
	v_add_f32_dpp v86, v86, v86 row_mirror row_mask:0xf bank_mask:0xf
	v_add_f32_dpp v87, v87, v87 row_mirror row_mask:0xf bank_mask:0xf
	s_and_saveexec_b64 s[94:95], s[10:11]
	s_cbranch_execz .LBB0_382
	ds_write_b128 v102, v[84:87]
